# diff_row phase: cross-row prefetch - the next row's loads are issued right after the current row's raw values are unpacked
# baseline (speedup 1.0000x reference)
.LBB0_25:
	s_and_b64 vcc, exec, s[2:3]
	s_cbranch_vccz .LBB0_29
	v_readlane_b32 s2, v254, 2
	v_readlane_b32 s1, v254, 33
	v_mov_b32_e32 v12, v191
	v_readlane_b32 s3, v254, 3
	v_mov_b32_e32 v0, s1
	ds_read_b32 v0, v0
	v_readlane_b32 s4, v254, 0
	v_readlane_b32 s5, v254, 1
	s_mov_b32 s1, s4
	v_and_b32_e32 v9, 63, v12
	s_waitcnt lgkmcnt(0)
	v_readfirstlane_b32 s6, v0
	v_mov_b32_e32 v0, s59
	ds_read_b32 v0, v0
	s_load_dwordx2 s[4:5], s[2:3], 0x80
	s_waitcnt lgkmcnt(0)
	v_lshlrev_b32_e32 v0, 2, v9
	global_load_dword v1, v0, s[4:5]
	global_load_dword v2, v0, s[4:5] offset:256
	global_load_dword v3, v0, s[4:5] offset:512
	global_load_dword v4, v0, s[4:5] offset:768
	v_xor_b32_e32 v16, 4, v0
	v_xor_b32_e32 v17, 8, v0
	v_xor_b32_e32 v18, 16, v0
	v_xor_b32_e32 v19, 32, v0
	v_readfirstlane_b32 s4, v12
	s_ashr_i32 s4, s4, 6
	s_lshl_b32 s5, s6, 3
	s_add_i32 s6, s5, s4
	s_cmp_gt_i32 s6, 0x87ff
	s_waitcnt vmcnt(2)
	v_mul_f32_e32 v5, v1, v2
	ds_bpermute_b32 v5, v16, v5
	s_waitcnt vmcnt(0)
	v_mul_f32_e32 v6, v3, v4
	ds_bpermute_b32 v6, v16, v6
	s_waitcnt lgkmcnt(1)
	v_fmac_f32_e32 v5, v1, v2
	ds_bpermute_b32 v1, v17, v5
	s_waitcnt lgkmcnt(1)
	v_fmac_f32_e32 v6, v3, v4
	ds_bpermute_b32 v2, v17, v6
	s_waitcnt lgkmcnt(1)
	v_add_f32_e32 v1, v5, v1
	ds_bpermute_b32 v3, v18, v1
	s_waitcnt lgkmcnt(1)
	v_add_f32_e32 v2, v6, v2
	ds_bpermute_b32 v4, v18, v2
	v_xor_b32_e32 v5, 64, v0
	v_xor_b32_e32 v0, 0x80, v0
	s_waitcnt lgkmcnt(1)
	v_add_f32_e32 v1, v1, v3
	ds_bpermute_b32 v3, v19, v1
	s_waitcnt lgkmcnt(1)
	v_add_f32_e32 v2, v2, v4
	ds_bpermute_b32 v4, v19, v2
	s_waitcnt lgkmcnt(1)
	v_add_f32_e32 v1, v1, v3
	ds_bpermute_b32 v3, v5, v1
	s_waitcnt lgkmcnt(1)
	v_add_f32_e32 v2, v2, v4
	ds_bpermute_b32 v4, v5, v2
	s_waitcnt lgkmcnt(1)
	v_add_f32_e32 v10, v1, v3
	ds_bpermute_b32 v13, v0, v10
	s_waitcnt lgkmcnt(1)
	v_add_f32_e32 v8, v2, v4
	ds_bpermute_b32 v11, v0, v8
	s_cbranch_scc1 .LBB0_29
	s_load_dwordx2 s[4:5], s[2:3], 0x88
	s_nop 0
	s_load_dwordx2 s[2:3], s[2:3], 0xc0
	v_lshlrev_b32_e32 v0, 5, v9
	v_and_b32_e32 v4, 0x1e0, v0
	s_waitcnt lgkmcnt(0)
	v_add_f32_e32 v10, v10, v13
	global_load_dwordx4 v[0:3], v4, s[4:5]
	s_nop 0
	global_load_dwordx4 v[4:7], v4, s[4:5] offset:16
	v_add_f32_e32 v8, v8, v11
	v_mul_f32_e32 v10, 0x3fb8aa3b, v10
	v_mul_f32_e32 v8, 0x3fb8aa3b, v8
	v_exp_f32_e32 v10, v10
	v_exp_f32_e32 v8, v8
	v_lshlrev_b32_e32 v9, 4, v9
	s_ashr_i32 s7, s6, 31
	v_lshlrev_b32_e32 v11, 4, v12
	v_sub_f32_e32 v8, v10, v8
	v_and_b32_e32 v10, 0x300, v9
	s_lshl_b64 s[4:5], s[6:7], 11
	v_and_b32_e32 v13, 0xf0, v11
	v_or3_b32 v10, s4, v10, v13
	v_mov_b32_e32 v11, s5
	v_lshl_add_u64 v[10:11], s[2:3], 0, v[10:11]
	s_mov_b64 s[4:5], 0xe400400
	v_and_b32_e32 v12, 48, v12
	v_lshl_add_u64 v[10:11], v[10:11], 0, s[4:5]
	s_lshl_b64 s[4:5], s[6:7], 12
	v_lshlrev_b32_e32 v12, 5, v12
	s_lshl_b32 s8, s1, 3
	v_or3_b32 v12, s4, v12, v13
	v_mov_b32_e32 v13, s5
	v_add_f32_e32 v8, 0x3eb60549, v8
	s_ashr_i32 s9, s8, 31
	v_lshl_add_u64 v[12:13], s[2:3], 0, v[12:13]
	s_mov_b64 s[2:3], 0x1f400800
	v_mov_b32_e32 v9, v8
	s_lshl_b64 s[10:11], s[8:9], 11
	v_lshl_add_u64 v[12:13], v[12:13], 0, s[2:3]
	s_lshl_b64 s[12:13], s[8:9], 12
	global_load_dwordx4 v[56:59], v[12:13], off offset:-2048
	global_load_dwordx4 v[60:63], v[12:13], off offset:-1792
	global_load_dwordx4 v[48:51], v[12:13], off
	global_load_dwordx4 v[52:55], v[12:13], off offset:256
	v_lshl_add_u64 v[12:13], v[12:13], 0, s[12:13]
.LBB0_28:
	s_add_i32 s6, s6, s8
	s_cmp_gt_i32 s6, 0x87ff
	s_waitcnt vmcnt(3)
	v_lshlrev_b32_e32 v14, 16, v59
	v_and_b32_e32 v15, 0xffff0000, v59
	s_waitcnt vmcnt(2)
	v_lshlrev_b32_e32 v28, 16, v63
	v_and_b32_e32 v29, 0xffff0000, v63
	v_pk_fma_f32 v[14:15], v[8:9], v[28:29], v[14:15] neg_lo:[1,0,0] neg_hi:[1,0,0]
	v_lshlrev_b32_e32 v28, 16, v58
	v_and_b32_e32 v29, 0xffff0000, v58
	v_lshlrev_b32_e32 v22, 16, v62
	v_and_b32_e32 v23, 0xffff0000, v62
	v_pk_fma_f32 v[22:23], v[8:9], v[22:23], v[28:29] neg_lo:[1,0,0] neg_hi:[1,0,0]
	v_mov_b32_e32 v26, v14
	v_mov_b32_e32 v27, v22
	v_pk_mul_f32 v[26:27], v[26:27], v[26:27]
	v_mov_b32_e32 v28, v15
	v_mov_b32_e32 v29, v23
	v_pk_fma_f32 v[26:27], v[28:29], v[28:29], v[26:27]
	v_lshlrev_b32_e32 v28, 16, v57
	v_and_b32_e32 v29, 0xffff0000, v57
	v_lshlrev_b32_e32 v30, 16, v61
	v_and_b32_e32 v31, 0xffff0000, v61
	v_lshlrev_b32_e32 v32, 16, v56
	v_and_b32_e32 v33, 0xffff0000, v56
	v_lshlrev_b32_e32 v20, 16, v60
	v_and_b32_e32 v21, 0xffff0000, v60
	global_load_dwordx4 v[56:59], v[12:13], off offset:-2048
	global_load_dwordx4 v[60:63], v[12:13], off offset:-1792
	v_pk_fma_f32 v[28:29], v[8:9], v[30:31], v[28:29] neg_lo:[1,0,0] neg_hi:[1,0,0]
	v_pk_fma_f32 v[20:21], v[8:9], v[20:21], v[32:33] neg_lo:[1,0,0] neg_hi:[1,0,0]
	v_pk_mul_f32 v[30:31], v[28:29], v[28:29]
	v_pk_mul_f32 v[24:25], v[20:21], v[20:21]
	v_add_f32_e32 v30, v31, v30
	v_add_f32_e32 v24, v25, v24
	v_add_f32_e32 v24, v24, v30
	v_add_f32_e32 v24, v27, v24
	v_add_f32_e32 v24, v26, v24
	ds_bpermute_b32 v25, v16, v24
	s_waitcnt lgkmcnt(0)
	v_add_f32_e32 v24, v24, v25
	ds_bpermute_b32 v25, v17, v24
	s_waitcnt lgkmcnt(0)
	v_add_f32_e32 v24, v24, v25
	ds_bpermute_b32 v25, v18, v24
	s_waitcnt lgkmcnt(0)
	v_add_f32_e32 v24, v24, v25
	ds_bpermute_b32 v25, v19, v24
	s_waitcnt lgkmcnt(0)
	v_add_f32_e32 v24, v24, v25
	v_fmamk_f32 v24, v24, 0x3c000000, v193
	v_cmp_gt_f32_e32 vcc, s67, v24
	v_mul_f32_e32 v25, 0x4f800000, v24
	s_nop 0
	v_cndmask_b32_e32 v24, v24, v25, vcc
	v_sqrt_f32_e32 v25, v24
	s_nop 0
	v_add_u32_e32 v26, -1, v25
	v_fma_f32 v27, -v26, v25, v24
	v_cmp_ge_f32_e64 s[2:3], 0, v27
	v_add_u32_e32 v27, 1, v25
	s_nop 0
	v_cndmask_b32_e64 v26, v25, v26, s[2:3]
	v_fma_f32 v25, -v27, v25, v24
	v_cmp_lt_f32_e64 s[2:3], 0, v25
	s_nop 1
	v_cndmask_b32_e64 v25, v26, v27, s[2:3]
	v_mul_f32_e32 v26, 0x37800000, v25
	v_cndmask_b32_e32 v25, v25, v26, vcc
	v_cmp_class_f32_e32 vcc, v24, v195
	s_nop 1
	v_cndmask_b32_e32 v24, v25, v24, vcc
	v_div_scale_f32 v25, s[2:3], v24, v24, 1.0
	v_rcp_f32_e32 v26, v25
	s_nop 0
	v_fma_f32 v27, -v25, v26, 1.0
	v_fmac_f32_e32 v26, v27, v26
	v_div_scale_f32 v27, vcc, 1.0, v24, 1.0
	v_mul_f32_e32 v30, v27, v26
	v_fma_f32 v31, -v25, v30, v27
	v_fmac_f32_e32 v30, v31, v26
	v_fma_f32 v25, -v25, v30, v27
	v_div_fmas_f32 v25, v25, v26, v30
	v_div_fixup_f32 v24, v25, v24, 1.0
	v_mul_f32_e32 v24, 0x3f24fd5c, v24
	v_pk_mul_f32 v[20:21], v[20:21], v[24:25] op_sel_hi:[1,0]
	v_pk_mul_f32 v[26:27], v[28:29], v[24:25] op_sel_hi:[1,0]
	v_pk_mul_f32 v[22:23], v[22:23], v[24:25] op_sel_hi:[1,0]
	v_pk_mul_f32 v[14:15], v[14:15], v[24:25] op_sel_hi:[1,0]
	v_pk_mul_f32 v[20:21], v[0:1], v[20:21]
	v_pk_mul_f32 v[26:27], v[2:3], v[26:27]
	v_pk_mul_f32 v[22:23], v[4:5], v[22:23]
	v_pk_mul_f32 v[14:15], v[6:7], v[14:15]
	v_cvt_pk_bf16_f32 v20, v20, v21
	v_cvt_pk_bf16_f32 v21, v26, v27
	v_cvt_pk_bf16_f32 v22, v22, v23
	v_cvt_pk_bf16_f32 v23, v14, v15
	global_store_dwordx4 v[10:11], v[20:23], off offset:-1024
	s_waitcnt vmcnt(4)
	v_lshlrev_b32_e32 v14, 16, v51
	v_and_b32_e32 v15, 0xffff0000, v51
	s_waitcnt vmcnt(3)
	v_lshlrev_b32_e32 v28, 16, v55
	v_and_b32_e32 v29, 0xffff0000, v55
	v_pk_fma_f32 v[14:15], v[8:9], v[28:29], v[14:15] neg_lo:[1,0,0] neg_hi:[1,0,0]
	v_lshlrev_b32_e32 v28, 16, v50
	v_and_b32_e32 v29, 0xffff0000, v50
	v_lshlrev_b32_e32 v22, 16, v54
	v_and_b32_e32 v23, 0xffff0000, v54
	v_pk_fma_f32 v[22:23], v[8:9], v[22:23], v[28:29] neg_lo:[1,0,0] neg_hi:[1,0,0]
	v_mov_b32_e32 v26, v14
	v_mov_b32_e32 v27, v22
	v_pk_mul_f32 v[26:27], v[26:27], v[26:27]
	v_mov_b32_e32 v28, v15
	v_mov_b32_e32 v29, v23
	v_pk_fma_f32 v[26:27], v[28:29], v[28:29], v[26:27]
	v_lshlrev_b32_e32 v28, 16, v49
	v_and_b32_e32 v29, 0xffff0000, v49
	v_lshlrev_b32_e32 v30, 16, v53
	v_and_b32_e32 v31, 0xffff0000, v53
	v_lshlrev_b32_e32 v32, 16, v48
	v_and_b32_e32 v33, 0xffff0000, v48
	v_lshlrev_b32_e32 v20, 16, v52
	v_and_b32_e32 v21, 0xffff0000, v52
	global_load_dwordx4 v[48:51], v[12:13], off
	global_load_dwordx4 v[52:55], v[12:13], off offset:256
	v_lshl_add_u64 v[12:13], v[12:13], 0, s[12:13]
	v_pk_fma_f32 v[28:29], v[8:9], v[30:31], v[28:29] neg_lo:[1,0,0] neg_hi:[1,0,0]
	v_pk_fma_f32 v[20:21], v[8:9], v[20:21], v[32:33] neg_lo:[1,0,0] neg_hi:[1,0,0]
	v_pk_mul_f32 v[30:31], v[28:29], v[28:29]
	v_pk_mul_f32 v[24:25], v[20:21], v[20:21]
	v_add_f32_e32 v30, v31, v30
	v_add_f32_e32 v24, v25, v24
	v_add_f32_e32 v24, v24, v30
	v_add_f32_e32 v24, v27, v24
	v_add_f32_e32 v24, v26, v24
	ds_bpermute_b32 v25, v16, v24
	s_waitcnt lgkmcnt(0)
	v_add_f32_e32 v24, v24, v25
	ds_bpermute_b32 v25, v17, v24
	s_waitcnt lgkmcnt(0)
	v_add_f32_e32 v24, v24, v25
	ds_bpermute_b32 v25, v18, v24
	s_waitcnt lgkmcnt(0)
	v_add_f32_e32 v24, v24, v25
	ds_bpermute_b32 v25, v19, v24
	s_waitcnt lgkmcnt(0)
	v_add_f32_e32 v24, v24, v25
	v_fmamk_f32 v24, v24, 0x3c000000, v193
	v_cmp_gt_f32_e32 vcc, s67, v24
	v_mul_f32_e32 v25, 0x4f800000, v24
	s_nop 0
	v_cndmask_b32_e32 v24, v24, v25, vcc
	v_sqrt_f32_e32 v25, v24
	s_nop 0
	v_add_u32_e32 v26, -1, v25
	v_fma_f32 v27, -v26, v25, v24
	v_cmp_ge_f32_e64 s[2:3], 0, v27
	v_add_u32_e32 v27, 1, v25
	s_nop 0
	v_cndmask_b32_e64 v26, v25, v26, s[2:3]
	v_fma_f32 v25, -v27, v25, v24
	v_cmp_lt_f32_e64 s[2:3], 0, v25
	s_nop 1
	v_cndmask_b32_e64 v25, v26, v27, s[2:3]
	v_mul_f32_e32 v26, 0x37800000, v25
	v_cndmask_b32_e32 v25, v25, v26, vcc
	v_cmp_class_f32_e32 vcc, v24, v195
	s_nop 1
	v_cndmask_b32_e32 v24, v25, v24, vcc
	v_div_scale_f32 v25, s[2:3], v24, v24, 1.0
	v_rcp_f32_e32 v26, v25
	s_nop 0
	v_fma_f32 v27, -v25, v26, 1.0
	v_fmac_f32_e32 v26, v27, v26
	v_div_scale_f32 v27, vcc, 1.0, v24, 1.0
	v_mul_f32_e32 v30, v27, v26
	v_fma_f32 v31, -v25, v30, v27
	v_fmac_f32_e32 v30, v31, v26
	v_fma_f32 v25, -v25, v30, v27
	v_div_fmas_f32 v25, v25, v26, v30
	v_div_fixup_f32 v24, v25, v24, 1.0
	v_mul_f32_e32 v24, 0x3f24fd5c, v24
	v_pk_mul_f32 v[20:21], v[20:21], v[24:25] op_sel_hi:[1,0]
	v_pk_mul_f32 v[26:27], v[28:29], v[24:25] op_sel_hi:[1,0]
	v_pk_mul_f32 v[22:23], v[22:23], v[24:25] op_sel_hi:[1,0]
	v_pk_mul_f32 v[14:15], v[14:15], v[24:25] op_sel_hi:[1,0]
	v_pk_mul_f32 v[20:21], v[0:1], v[20:21]
	v_pk_mul_f32 v[26:27], v[2:3], v[26:27]
	v_pk_mul_f32 v[22:23], v[4:5], v[22:23]
	v_pk_mul_f32 v[14:15], v[6:7], v[14:15]
	v_cvt_pk_bf16_f32 v20, v20, v21
	v_cvt_pk_bf16_f32 v21, v26, v27
	v_cvt_pk_bf16_f32 v22, v22, v23
	v_cvt_pk_bf16_f32 v23, v14, v15
	global_store_dwordx4 v[10:11], v[20:23], off
	v_lshl_add_u64 v[10:11], v[10:11], 0, s[10:11]
	s_cbranch_scc0 .LBB0_28
	s_waitcnt vmcnt(0)
